# per-XCD attention work queues (batch b = XCD b): all grid barriers XCD-local except after prep and after each layer's last phase (4 global + 27 local)
# speedup vs baseline: 1.0583x; 1.0174x over previous
; DI int otid_w(int gw) { return (gw << 6) | olane(); }
; DI float uni(float x) { return __builtin_bit_cast(float, __builtin_amdgcn_readfirstlane(__builtin_bit_cast(int, x))); }
; DI void attn_phase(const Params& p, const int j, char* lds, const int cidx) {
;     ...
;     unsigned* counter = (unsigned*)(ws + OFF_CTRL) + cidx;
;     int* s_item = (int*)(lds + LDS_BYTES - 16);
;     const int tid = otid_w(p.wave), lane = tid & 63, w = tid >> 6, l31 = lane & 31, hh = lane >> 5;
;     const float lambda_init = (j == 0) ? 0.2f : 0.4707130183435842f;
;     float lam;
;     {
;         const float* lp = p.att_lambda + (size_t)j * 4 * 64;
;         const float sa = wave_sum(lp[lane] * lp[64 + lane]), sb = wave_sum(lp[128 + lane] * lp[192 + lane]);
;         lam = uni(__expf(sa) - __expf(sb) + lambda_init);
;     }
;     const float* subln = p.att_subln + (size_t)j * 128;
.LBB0_195:
	s_and_b64 vcc, exec, s[4:5]
	s_cbranch_vccz .LBB0_319
	v_readlane_b32 s6, v255, 4
	v_readlane_b32 s7, v255, 5
	s_add_u32 s30, s68, 0xe681000
	s_mov_b32 s7, s89
	s_addc_u32 s31, s69, 0
	s_lshl_b64 s[4:5], s[6:7], 2
	s_add_u32 s16, s68, s4
	s_mov_b32 s4, s6
	s_addc_u32 s17, s69, s5
	v_writelane_b32 v255, s4, 4
	s_lshr_b32 s98, s6, 1
	s_and_b32 s98, s98, 8
	s_and_b32 s99, s2, 7
	s_add_i32 s98, s98, s99
	s_lshl_b32 s98, s98, 2
	s_add_u32 s16, s68, s98
	s_addc_u32 s17, s69, 0
	s_add_u32 s16, s16, 0x80
	s_addc_u32 s17, s17, 0
	s_cmp_lt_u32 s6, 15
	s_cselect_b64 vcc, -1, 0
	v_writelane_b32 v255, s5, 5
	s_waitcnt vmcnt(0)
	v_mbcnt_lo_u32_b32 v0, -1, 0
	v_mbcnt_hi_u32_b32 v0, -1, v0
	v_mov_b32_e32 v4, 0x3ef1014c
	v_readlane_b32 s6, v255, 10
	v_readlane_b32 s7, v255, 11
	s_mov_b32 s7, s89
	s_lshl_b64 s[4:5], s[6:7], 10
	v_and_b32_e32 v2, 63, v0
	s_add_u32 s4, s46, s4
	v_mov_b32_e32 v5, 0x3e4ccccd
	s_addc_u32 s5, s47, s5
	v_lshlrev_b32_e32 v2, 2, v2
	v_cndmask_b32_e32 v4, v4, v5, vcc
	global_load_dword v5, v2, s[4:5]
	global_load_dword v6, v2, s[4:5] offset:256
	v_mbcnt_lo_u32_b32 v8, -1, 0
	v_mbcnt_hi_u32_b32 v8, -1, v8
	v_or_b32_e32 v1, s71, v0
	v_lshlrev_b32_e32 v8, 2, v8
	v_bitop3_b32 v8, v8, s78, v199 bitop3:0x6c
	v_bfe_u32 v3, v0, 5, 1
	v_lshlrev_b32_e32 v160, 2, v1
	v_lshlrev_b32_e32 v32, 4, v3
	v_cmp_eq_u32_e64 s[12:13], 0, v1
	v_lshlrev_b32_e32 v138, 2, v3
	v_add_u32_e32 v161, 0xd000, v160
	v_sub_f32_e32 v162, 1.0, v4
	v_lshl_add_u64 v[142:143], s[86:87], 0, v[32:33]
	s_waitcnt vmcnt(0)
	v_mul_f32_e32 v7, v5, v6
	ds_bpermute_b32 v7, v8, v7
	s_waitcnt lgkmcnt(0)
	v_fmac_f32_e32 v7, v5, v6
	v_mbcnt_lo_u32_b32 v5, -1, 0
	v_mbcnt_hi_u32_b32 v5, -1, v5
	v_mbcnt_lo_u32_b32 v6, -1, 0
	v_mbcnt_hi_u32_b32 v6, -1, v6
	s_nop 0
	v_lshlrev_b32_e32 v5, 2, v5
	v_bitop3_b32 v5, v5, 64, v199 bitop3:0x6c
	ds_bpermute_b32 v5, v5, v7
	v_lshlrev_b32_e32 v6, 2, v6
	v_bitop3_b32 v6, v6, 32, v199 bitop3:0x6c
	s_waitcnt lgkmcnt(0)
	v_add_f32_e32 v5, v7, v5
	ds_bpermute_b32 v6, v6, v5
	s_waitcnt lgkmcnt(0)
	v_add_f32_e32 v5, v5, v6
	v_mbcnt_lo_u32_b32 v6, -1, 0
	v_mbcnt_hi_u32_b32 v6, -1, v6
	s_nop 0
	v_lshlrev_b32_e32 v6, 2, v6
	v_bitop3_b32 v6, v6, 16, v199 bitop3:0x6c
	ds_bpermute_b32 v6, v6, v5
	s_waitcnt lgkmcnt(0)
	v_add_f32_e32 v5, v5, v6
	v_mbcnt_lo_u32_b32 v6, -1, 0
	v_mbcnt_hi_u32_b32 v6, -1, v6
	s_nop 0
	v_lshlrev_b32_e32 v6, 2, v6
	v_bitop3_b32 v6, v6, 8, v199 bitop3:0x6c
	ds_bpermute_b32 v6, v6, v5
	s_waitcnt lgkmcnt(0)
	v_add_f32_e32 v5, v5, v6
	v_mbcnt_lo_u32_b32 v6, -1, 0
	v_mbcnt_hi_u32_b32 v6, -1, v6
	s_nop 0
	v_lshlrev_b32_e32 v6, 2, v6
	v_bitop3_b32 v6, v6, 4, v199 bitop3:0x6c
	ds_bpermute_b32 v6, v6, v5
	s_waitcnt lgkmcnt(0)
	v_add_f32_e32 v5, v5, v6
	global_load_dword v6, v2, s[4:5] offset:512
	s_nop 0
	global_load_dword v2, v2, s[4:5] offset:768
	v_mbcnt_lo_u32_b32 v8, -1, 0
	v_mbcnt_hi_u32_b32 v8, -1, v8
	v_mul_f32_e32 v5, 0x3fb8aa3b, v5
	v_lshlrev_b32_e32 v8, 2, v8
	v_bitop3_b32 v8, v8, s78, v199 bitop3:0x6c
	v_exp_f32_e32 v5, v5
	s_mov_b32 s4, s6
	v_writelane_b32 v255, s4, 10
	s_waitcnt vmcnt(0)
	v_mul_f32_e32 v7, v6, v2
	ds_bpermute_b32 v7, v8, v7
	v_writelane_b32 v255, s5, 11
	s_lshl_b64 s[4:5], s[6:7], 9
	s_add_u32 s4, s48, s4
	s_movk_i32 s6, 0xffe0
	s_waitcnt lgkmcnt(0)
	v_fmac_f32_e32 v7, v6, v2
	v_mbcnt_lo_u32_b32 v2, -1, 0
	v_mbcnt_hi_u32_b32 v2, -1, v2
	v_mbcnt_lo_u32_b32 v6, -1, 0
	v_mbcnt_hi_u32_b32 v6, -1, v6
	s_addc_u32 s5, s49, s5
	v_lshlrev_b32_e32 v2, 2, v2
	v_bitop3_b32 v2, v2, 64, v199 bitop3:0x6c
	ds_bpermute_b32 v2, v2, v7
	v_lshlrev_b32_e32 v6, 2, v6
	v_bitop3_b32 v6, v6, 32, v199 bitop3:0x6c
	v_lshl_add_u64 v[140:141], s[4:5], 0, v[32:33]
	s_waitcnt lgkmcnt(0)
	v_add_f32_e32 v2, v7, v2
	ds_bpermute_b32 v6, v6, v2
	s_waitcnt lgkmcnt(0)
	v_add_f32_e32 v2, v2, v6
	v_mbcnt_lo_u32_b32 v6, -1, 0
	v_mbcnt_hi_u32_b32 v6, -1, v6
	s_nop 0
	v_lshlrev_b32_e32 v6, 2, v6
	v_bitop3_b32 v6, v6, 16, v199 bitop3:0x6c
	ds_bpermute_b32 v6, v6, v2
	s_waitcnt lgkmcnt(0)
	v_add_f32_e32 v2, v2, v6
	v_mbcnt_lo_u32_b32 v6, -1, 0
	v_mbcnt_hi_u32_b32 v6, -1, v6
	s_nop 0
	v_lshlrev_b32_e32 v6, 2, v6
	v_bitop3_b32 v6, v6, 8, v199 bitop3:0x6c
	ds_bpermute_b32 v6, v6, v2
	s_waitcnt lgkmcnt(0)
	v_add_f32_e32 v2, v2, v6
	v_mbcnt_lo_u32_b32 v6, -1, 0
	v_mbcnt_hi_u32_b32 v6, -1, v6
	s_nop 0
	v_lshlrev_b32_e32 v6, 2, v6
	v_bitop3_b32 v6, v6, 4, v199 bitop3:0x6c
	ds_bpermute_b32 v6, v6, v2
	s_waitcnt lgkmcnt(0)
	v_add_f32_e32 v2, v2, v6
	v_mul_f32_e32 v2, 0x3fb8aa3b, v2
	v_exp_f32_e32 v2, v2
	s_nop 0
	v_sub_f32_e32 v2, v5, v2
	v_add_f32_e32 v2, v4, v2
	s_nop 0
	v_readfirstlane_b32 s18, v2
	v_ashrrev_i32_e32 v2, 1, v1
	v_bfi_b32 v139, s6, v2, v0
	v_lshlrev_b32_e32 v0, 3, v3
	s_mov_b32 s19, s18
	v_lshlrev_b32_e32 v144, 1, v0
	s_branch .LBB0_200

; DI void attn_phase(const Params& p, const int j, char* lds, const int cidx) {
;     ...
;         if (tid == 0) *s_item = (int)atomicAdd(counter, 1u);
;         __syncthreads();
;         const int item = *s_item;
;         __syncthreads();
;         if (item >= 768) break;
;         if (item < 256) {
;             const int qt = 7 - (item >> 5), r = item & 31, b = r >> 2, h = r & 3;
;     ...
;             const int jj = item - 256;
;             const int qt = 7 - (jj >> 6), r = jj & 63, b = r >> 3, h = r & 7;
.LBB0_200:
	s_and_saveexec_b64 s[4:5], s[12:13]
	s_cbranch_execz .LBB0_202
	v_mov_b64_e32 v[0:1], s[16:17]
	v_mov_b32_e32 v2, 1
	flat_atomic_add v0, v[0:1], v2 sc0
	s_waitcnt vmcnt(0) lgkmcnt(0)
	v_readfirstlane_b32 s99, v0
	s_and_b32 s98, s2, 7
	s_cmp_lt_u32 s99, 32
	s_cbranch_scc0 .Lq_a
	s_lshr_b32 vcc_lo, s99, 2
	s_lshl_b32 vcc_lo, vcc_lo, 5
	s_and_b32 vcc_hi, s99, 3
	s_or_b32 vcc_lo, vcc_lo, vcc_hi
	s_lshl_b32 vcc_hi, s98, 2
	s_or_b32 s99, vcc_lo, vcc_hi
	s_branch .Lq_done
.Lq_a:
	s_cmp_lt_u32 s99, 96
	s_cbranch_scc1 .Lq_a2
	s_movk_i32 s99, 0x300
	s_branch .Lq_done
.Lq_a2:
	s_sub_u32 s99, s99, 32
	s_lshr_b32 vcc_lo, s99, 3
	s_lshl_b32 vcc_lo, vcc_lo, 6
	s_and_b32 vcc_hi, s99, 7
	s_or_b32 vcc_lo, vcc_lo, vcc_hi
	s_lshl_b32 vcc_hi, s98, 3
	s_or_b32 vcc_lo, vcc_lo, vcc_hi
	s_add_u32 s99, vcc_lo, 0x100
.Lq_done:
	v_mov_b32_e32 v0, s99
	ds_write_b32 v198, v0

; DI unsigned xb_ld(unsigned* p)              { return __hip_atomic_load(p, __ATOMIC_RELAXED, __HIP_MEMORY_SCOPE_AGENT); }
; DI unsigned xb_add(unsigned* p, unsigned v) { return __hip_atomic_fetch_add(p, v, __ATOMIC_RELAXED, __HIP_MEMORY_SCOPE_AGENT); }
; #define XB_SPIN(cond, bar) do { unsigned _sp = 0; while (cond) { __builtin_amdgcn_s_sleep(1); \
;     if ((++_sp & 255u) == 0u) { if (xb_ld(&(bar)[XB_TMO])) break; if (_sp > XB_SPIN_CAP) { atomicAdd(&(bar)[XB_TMO], 1u); break; } } } } while (0)
; DI void xcd_barrier(const XcdBarrier& b, const int gw) {
;     ...
;         const unsigned old = xb_add(&bar[XB_XSUB(b.x)], 1u);
;         const unsigned gen = old / nloc;
;         if (old + 1u == (gen + 1u) * nloc) {
;             __builtin_amdgcn_fence(__ATOMIC_RELEASE, "agent");
;             asm volatile("s_waitcnt vmcnt(0)" ::: "memory");
;             const unsigned og = xb_add(&bar[XB_TOP], 1u);
;             const unsigned tg = og / nx;
;             if (og + 1u == (tg + 1u) * nx) xb_add(&bar[XB_TOPGEN], 1u);
;             else XB_SPIN(xb_ld(&bar[XB_TOPGEN]) == tg, bar);
;             __builtin_amdgcn_fence(__ATOMIC_ACQUIRE, "agent");
;             xb_add(&bar[XB_XGEN(b.x)], 1u);
.LBB0_528:
	s_andn2_saveexec_b64 s[8:9], s[8:9]
	s_cbranch_execz .LBB0_548
	s_mov_b64 s[8:9], exec
	s_add_i32 s98, s36, -1
	s_lshr_b32 s98, 0x1fdfbf7e, s98
	s_bitcmp1_b32 s98, 0
	s_cbranch_scc0 .Lxb_global
	v_mov_b32_e32 v1, 0x20048
	ds_read_b32 v1, v1
	s_waitcnt lgkmcnt(0)
	v_readfirstlane_b32 s98, v1
	s_cmp_lg_u32 s98, 0
	s_cbranch_scc1 .LBB0_545
